# GQA fast path staging addresses also formed with one 64-bit VALU add against an SGPR-pair constant (drops 3 add_co/addc pairs and their s_nop pads per two tiles)
# speedup vs baseline: 1.0060x; 1.0016x over previous
; __device__ __forceinline__ void finishSM(f32x16& p0, f32x16& p1, float alpha, float& l_reg, bf16x8& pa0, bf16x8& pa1, bf16x8& pa2, bf16x8& pa3) {
; #pragma unroll
;   for (int r = 0; r < 16; ++r) p1[r] = __builtin_amdgcn_exp2f(p1[r]);
;   float ps = 0;
; #pragma unroll
;   for (int r = 0; r < 16; ++r) ps += p0[r];
; #pragma unroll
;   for (int r = 0; r < 16; ++r) ps += p1[r];
;   { auto rr = __builtin_amdgcn_permlane32_swap(__float_as_uint(ps), __float_as_uint(ps), false, false);
;     ps = __uint_as_float(rr[0]) + __uint_as_float(rr[1]); }
;   l_reg = l_reg * alpha + ps;
;     ...
;   PK4(p0, 0, pa0); PK4(p0, 8, pa1); PK4(p1, 0, pa2); PK4(p1, 8, pa3);
;     ...
; }
; template <int DQK> __device__ __forceinline__ void qkt(f32x16& p0, f32x16& p1, const char* Ks, const bf16x8* qr, int r32, int hi, const f32x16& negm) {
; #pragma unroll
;   for (int d0 = 0; d0 < DQK / 16; ++d0) { const int cb = (d0 * 16 + hi * 8) * 2;
;     const bf16x8 b0 = *reinterpret_cast<const bf16x8*>(Ks + (DQK == 128 ? KSWZ(r32, cb) : KSWZ64(r32, cb)));
;     const bf16x8 b1 = *reinterpret_cast<const bf16x8*>(Ks + (DQK == 128 ? KSWZ(32 + r32, cb) : KSWZ64(32 + r32, cb)));
;     if (d0 == 0) { p0 = __builtin_amdgcn_mfma_f32_32x32x16_bf16(b0, qr[0], negm, 0, 0, 0); p1 = __builtin_amdgcn_mfma_f32_32x32x16_bf16(b1, qr[0], negm, 0, 0, 0); }
;     else { p0 = __builtin_amdgcn_mfma_f32_32x32x16_bf16(b0, qr[d0], p0, 0, 0, 0); p1 = __builtin_amdgcn_mfma_f32_32x32x16_bf16(b1, qr[d0], p1, 0, 0, 0); } }
; }
; template <bool BIAS, bool VIRT> __device__ __forceinline__ void fixup(f32x16& p0, f32x16& p1, int t, int L, int qw0, int r32, int hi, const float* lut) {
;     ...
;   if (__builtin_expect(k0 + KVBLK > L, 0)) {
.LBB0_69:
	s_add_i32 s99, s12, 64
	s_cmp_le_u32 s99, s16
	s_cbranch_scc0 .Lslow_g1
	ds_read_b128 v[198:201], v195 offset:57344
	ds_read_b128 v[202:205], v195 offset:49152
	ds_read_b128 v[244:247], v211 offset:57344
	ds_read_b128 v[206:209], v211 offset:49152
	v_add_f32_e32 v227, 0, v238
	v_add_f32_e32 v227, v240, v227
	v_cvt_pk_bf16_f32 v66, v238, v240
	v_add_f32_e32 v227, v236, v227
	v_add_f32_e32 v227, v239, v227
	v_cvt_pk_bf16_f32 v67, v236, v239
	v_add_f32_e32 v227, v235, v227
	v_add_f32_e32 v227, v237, v227
	v_cvt_pk_bf16_f32 v68, v235, v237
	v_add_f32_e32 v227, v233, v227
	v_add_f32_e32 v227, v234, v227
	v_cvt_pk_bf16_f32 v69, v233, v234
	s_waitcnt lgkmcnt(3)
	v_mfma_f32_32x32x16_bf16 v[114:129], v[198:201], v[174:177], v[82:97]
	v_add_f32_e32 v227, v184, v227
	v_add_f32_e32 v227, v232, v227
	v_cvt_pk_bf16_f32 v70, v184, v232
	v_add_f32_e32 v227, v183, v227
	v_add_f32_e32 v227, v185, v227
	s_waitcnt lgkmcnt(2)
	v_mfma_f32_32x32x16_bf16 v[130:145], v[202:205], v[174:177], v[82:97]
	ds_read_b128 v[198:201], v210 offset:57344
	ds_read_b128 v[202:205], v210 offset:49152
	v_cvt_pk_bf16_f32 v71, v183, v185
	v_add_f32_e32 v227, v180, v227
	v_add_f32_e32 v227, v182, v227
	v_cvt_pk_bf16_f32 v72, v180, v182
	v_add_f32_e32 v227, v179, v227
	s_waitcnt lgkmcnt(3)
	v_mfma_f32_32x32x16_bf16 v[114:129], v[244:247], v[170:173], v[114:129]
	v_add_f32_e32 v227, v181, v227
	v_cvt_pk_bf16_f32 v73, v179, v181
	v_exp_f32_e32 v98, v98
	v_exp_f32_e32 v99, v99
	v_permlane32_swap_b32_e32 v66, v68
	s_waitcnt lgkmcnt(2)
	v_mfma_f32_32x32x16_bf16 v[130:145], v[206:209], v[170:173], v[130:145]
	ds_read_b128 v[244:247], v197 offset:57344
	ds_read_b128 v[206:209], v197 offset:49152
	v_permlane32_swap_b32_e32 v67, v69
	v_permlane32_swap_b32_e32 v70, v72
	v_permlane32_swap_b32_e32 v71, v73
	v_exp_f32_e32 v100, v100
	v_add_f32_e32 v227, v98, v227
	s_waitcnt lgkmcnt(3)
	v_mfma_f32_32x32x16_bf16 v[114:129], v[198:201], v[166:169], v[114:129]
	v_exp_f32_e32 v101, v101
	v_add_f32_e32 v227, v99, v227
	v_exp_f32_e32 v102, v102
	v_add_f32_e32 v227, v100, v227
	s_waitcnt lgkmcnt(2)
	v_mfma_f32_32x32x16_bf16 v[130:145], v[202:205], v[166:169], v[130:145]
	ds_read_b128 v[198:201], v196 offset:57344
	ds_read_b128 v[202:205], v196 offset:49152
	v_exp_f32_e32 v103, v103
	v_add_f32_e32 v227, v101, v227
	v_exp_f32_e32 v104, v104
	v_add_f32_e32 v227, v102, v227
	s_waitcnt lgkmcnt(3)
	v_mfma_f32_32x32x16_bf16 v[114:129], v[244:247], v[162:165], v[114:129]
	v_exp_f32_e32 v105, v105
	v_add_f32_e32 v227, v103, v227
	v_exp_f32_e32 v106, v106
	v_add_f32_e32 v227, v104, v227
	s_waitcnt lgkmcnt(2)
	v_mfma_f32_32x32x16_bf16 v[130:145], v[206:209], v[162:165], v[130:145]
	ds_read_b128 v[244:247], v222 offset:57344
	ds_read_b128 v[206:209], v222 offset:49152
	v_exp_f32_e32 v107, v107
	v_add_f32_e32 v227, v105, v227
	v_exp_f32_e32 v108, v108
	v_add_f32_e32 v227, v106, v227
	s_waitcnt lgkmcnt(3)
	v_mfma_f32_32x32x16_bf16 v[114:129], v[198:201], v[158:161], v[114:129]
	v_exp_f32_e32 v109, v109
	v_add_f32_e32 v227, v107, v227
	v_exp_f32_e32 v110, v110
	v_add_f32_e32 v227, v108, v227
	s_waitcnt lgkmcnt(2)
	v_mfma_f32_32x32x16_bf16 v[130:145], v[202:205], v[158:161], v[130:145]
	ds_read_b128 v[198:201], v223 offset:57344
	ds_read_b128 v[202:205], v223 offset:49152
	v_exp_f32_e32 v111, v111
	v_add_f32_e32 v227, v109, v227
	v_exp_f32_e32 v112, v112
	v_add_f32_e32 v227, v110, v227
	s_waitcnt lgkmcnt(3)
	v_mfma_f32_32x32x16_bf16 v[114:129], v[244:247], v[154:157], v[114:129]
	v_exp_f32_e32 v113, v113
	v_add_f32_e32 v227, v111, v227
	v_add_f32_e32 v227, v112, v227
	v_add_f32_e32 v227, v113, v227
	s_waitcnt lgkmcnt(2)
	v_mfma_f32_32x32x16_bf16 v[130:145], v[206:209], v[154:157], v[130:145]
	ds_read_b128 v[244:247], v224 offset:57344
	ds_read_b128 v[206:209], v224 offset:49152
	v_mov_b32_e32 v228, v227
	v_cvt_pk_bf16_f32 v74, v98, v99
	v_cvt_pk_bf16_f32 v75, v100, v101
	v_cvt_pk_bf16_f32 v76, v102, v103
	s_waitcnt lgkmcnt(3)
	v_mfma_f32_32x32x16_bf16 v[114:129], v[198:201], v[150:153], v[114:129]
	v_cvt_pk_bf16_f32 v77, v104, v105
	v_cvt_pk_bf16_f32 v78, v106, v107
	v_cvt_pk_bf16_f32 v79, v108, v109
	v_cvt_pk_bf16_f32 v80, v110, v111
	s_waitcnt lgkmcnt(2)
; #define SBAR() __builtin_amdgcn_sched_barrier(0)
; template <bool FIRST> __device__ __forceinline__ void partialSM(f32x16& p0, f32x16& p1, float& m_reg, float& alpha, f32x16& negm, float c_cur) {
;   float pmax = p0[0];
; #pragma unroll
;   for (int r = 1; r < 16; ++r) pmax = fmaxf(pmax, p0[r]);
; #pragma unroll
;   for (int r = 0; r < 16; ++r) pmax = fmaxf(pmax, p1[r]);
;   { auto rr = __builtin_amdgcn_permlane32_swap(__float_as_uint(pmax), __float_as_uint(pmax), false, false);
;     pmax = fmaxf(__uint_as_float(rr[0]), __uint_as_float(rr[1])); }
; template <int D0> __device__ __forceinline__ void pv_one(f32x16& od, int vb, bf16x8 pa0, bf16x8 pa1, bf16x8 pa2, bf16x8 pa3) {
;   const s16x4 l0 = tr_read<v_rd_off(D0, 0, 0)>(vb), h0 = tr_read<v_rd_off(D0, 0, 1)>(vb), l1 = tr_read<v_rd_off(D0, 1, 0)>(vb), h1 = tr_read<v_rd_off(D0, 1, 1)>(vb);
;   const s16x4 l2 = tr_read<v_rd_off(D0, 2, 0)>(vb), h2 = tr_read<v_rd_off(D0, 2, 1)>(vb), l3 = tr_read<v_rd_off(D0, 3, 0)>(vb), h3 = tr_read<v_rd_off(D0, 3, 1)>(vb);
;   asm volatile("s_waitcnt lgkmcnt(0)" ::: "memory"); SBAR();
;     ...
;   od = __builtin_amdgcn_mfma_f32_32x32x16_bf16(pa0, PK(l0, h0), od, 0, 0, 0);
;   od = __builtin_amdgcn_mfma_f32_32x32x16_bf16(pa1, PK(l1, h1), od, 0, 0, 0);
;   od = __builtin_amdgcn_mfma_f32_32x32x16_bf16(pa2, PK(l2, h2), od, 0, 0, 0);
;   od = __builtin_amdgcn_mfma_f32_32x32x16_bf16(pa3, PK(l3, h3), od, 0, 0, 0);
;     ...
; }
; __device__ __forceinline__ void pv_d0(f32x16* o, int vb, bf16x8 pa0, bf16x8 pa1, bf16x8 pa2, bf16x8 pa3) {
;   pv_one<0>(o[0], vb, pa0, pa1, pa2, pa3); pv_one<1>(o[1], vb, pa0, pa1, pa2, pa3); pv_one<2>(o[2], vb, pa0, pa1, pa2, pa3); pv_one<3>(o[3], vb, pa0, pa1, pa2, pa3);
	v_mfma_f32_32x32x16_bf16 v[130:145], v[202:205], v[150:153], v[130:145]
	ds_read_b64_tr_b16 v[178:179], v193 offset:0
	ds_read_b64_tr_b16 v[180:181], v193 offset:0x800
	ds_read_b64_tr_b16 v[182:183], v193 offset:0x200
	ds_read_b64_tr_b16 v[184:185], v193 offset:0xa00
	ds_read_b64_tr_b16 v[198:199], v193 offset:0x400
	ds_read_b64_tr_b16 v[200:201], v193 offset:0xc00
	ds_read_b64_tr_b16 v[202:203], v193 offset:0x600
	ds_read_b64_tr_b16 v[204:205], v193 offset:0xe00
	v_cvt_pk_bf16_f32 v81, v112, v113
	v_permlane32_swap_b32_e32 v227, v228
	v_permlane32_swap_b32_e32 v74, v76
	v_permlane32_swap_b32_e32 v75, v77
	s_waitcnt lgkmcnt(9)
	v_mfma_f32_32x32x16_bf16 v[114:129], v[244:247], v[146:149], v[114:129]
	v_permlane32_swap_b32_e32 v78, v80
	v_permlane32_swap_b32_e32 v79, v81
	s_mov_b64 s[98:99], 0x48000
	v_lshl_add_u64 v[218:219], v[186:187], 0, s[98:99]
	s_waitcnt lgkmcnt(8)
	v_mfma_f32_32x32x16_bf16 v[130:145], v[206:209], v[146:149], v[130:145]
	global_load_dwordx4 v[98:101], v[186:187], off offset:512
	global_load_dwordx4 v[102:105], v[186:187], off
	global_load_dwordx4 v[110:113], v[218:219], off offset:512
	global_load_dwordx4 v[106:109], v[218:219], off
	s_waitcnt lgkmcnt(6)
	v_mfma_f32_32x32x16_bf16 v[2:17], v[66:69], v[178:181], v[2:17]
	ds_read_b64_tr_b16 v[178:179], v193 offset:0x1000
	ds_read_b64_tr_b16 v[180:181], v193 offset:0x1800
	s_waitcnt lgkmcnt(6)
	v_mfma_f32_32x32x16_bf16 v[50:65], v[66:69], v[182:185], v[50:65]
	ds_read_b64_tr_b16 v[182:183], v193 offset:0x1200
	ds_read_b64_tr_b16 v[184:185], v193 offset:0x1a00
	s_waitcnt lgkmcnt(6)
	v_mfma_f32_32x32x16_bf16 v[34:49], v[66:69], v[198:201], v[34:49]
	ds_read_b64_tr_b16 v[198:199], v193 offset:0x1400
	ds_read_b64_tr_b16 v[200:201], v193 offset:0x1c00
	s_waitcnt lgkmcnt(6)
	v_mfma_f32_32x32x16_bf16 v[18:33], v[66:69], v[202:205], v[18:33]
	ds_read_b64_tr_b16 v[202:203], v193 offset:0x1600
	ds_read_b64_tr_b16 v[204:205], v193 offset:0x1e00
	s_waitcnt lgkmcnt(6)
	v_mfma_f32_32x32x16_bf16 v[2:17], v[70:73], v[178:181], v[2:17]
	ds_read_b64_tr_b16 v[178:179], v193 offset:0x2000
	ds_read_b64_tr_b16 v[180:181], v193 offset:0x2800
	v_max_f32_e32 v218, v130, v131
	v_max3_f32 v218, v218, v132, v133
	s_waitcnt lgkmcnt(6)
	v_mfma_f32_32x32x16_bf16 v[50:65], v[70:73], v[182:185], v[50:65]
	ds_read_b64_tr_b16 v[182:183], v193 offset:0x2200
	ds_read_b64_tr_b16 v[184:185], v193 offset:0x2a00
	v_max3_f32 v218, v218, v134, v135
	v_max3_f32 v218, v218, v136, v137
	s_waitcnt lgkmcnt(6)
	v_mfma_f32_32x32x16_bf16 v[34:49], v[70:73], v[198:201], v[34:49]
	ds_read_b64_tr_b16 v[198:199], v193 offset:0x2400
	ds_read_b64_tr_b16 v[200:201], v193 offset:0x2c00
	v_max3_f32 v218, v218, v138, v139
	v_max3_f32 v218, v218, v140, v141
	s_waitcnt lgkmcnt(6)
	v_mfma_f32_32x32x16_bf16 v[18:33], v[70:73], v[202:205], v[18:33]
	ds_read_b64_tr_b16 v[202:203], v193 offset:0x2600
	ds_read_b64_tr_b16 v[204:205], v193 offset:0x2e00
	v_max3_f32 v218, v218, v142, v143
	v_max3_f32 v218, v218, v144, v145
	s_waitcnt lgkmcnt(6)
	v_mfma_f32_32x32x16_bf16 v[2:17], v[74:77], v[178:181], v[2:17]
	ds_read_b64_tr_b16 v[178:179], v193 offset:0x3000
	ds_read_b64_tr_b16 v[180:181], v193 offset:0x3800
	v_max3_f32 v218, v218, v114, v115
	v_max3_f32 v218, v218, v116, v117
	s_waitcnt lgkmcnt(6)
	v_mfma_f32_32x32x16_bf16 v[50:65], v[74:77], v[182:185], v[50:65]
	ds_read_b64_tr_b16 v[182:183], v193 offset:0x3200
	ds_read_b64_tr_b16 v[184:185], v193 offset:0x3a00
	v_max3_f32 v218, v218, v118, v119
	v_max3_f32 v218, v218, v120, v121
	s_waitcnt lgkmcnt(6)
	v_mfma_f32_32x32x16_bf16 v[34:49], v[74:77], v[198:201], v[34:49]
	ds_read_b64_tr_b16 v[198:199], v193 offset:0x3400
	ds_read_b64_tr_b16 v[200:201], v193 offset:0x3c00
	v_max3_f32 v218, v218, v122, v123
	s_waitcnt lgkmcnt(6)
	v_mfma_f32_32x32x16_bf16 v[18:33], v[74:77], v[202:205], v[18:33]
	ds_read_b64_tr_b16 v[202:203], v193 offset:0x3600
	ds_read_b64_tr_b16 v[204:205], v193 offset:0x3e00
	v_max3_f32 v218, v218, v124, v125
	s_waitcnt lgkmcnt(6)
	v_mfma_f32_32x32x16_bf16 v[2:17], v[78:81], v[178:181], v[2:17]
	v_max3_f32 v218, v218, v126, v127
	s_waitcnt lgkmcnt(4)
	v_mfma_f32_32x32x16_bf16 v[50:65], v[78:81], v[182:185], v[50:65]
	v_max3_f32 v218, v218, v128, v129
	s_waitcnt lgkmcnt(2)
	v_mfma_f32_32x32x16_bf16 v[34:49], v[78:81], v[198:201], v[34:49]
	v_mov_b32_e32 v219, v218
	s_waitcnt lgkmcnt(0)
	v_mfma_f32_32x32x16_bf16 v[18:33], v[78:81], v[202:205], v[18:33]
	v_permlane32_swap_b32_e32 v218, v219
	v_max_f32_e32 v66, v218, v219

; template <bool FIRST> __device__ __forceinline__ void partialSM(f32x16& p0, f32x16& p1, float& m_reg, float& alpha, f32x16& negm, float c_cur) {
;     ...
;   for (int r = 0; r < 16; ++r) p0[r] = __builtin_amdgcn_exp2f(p0[r]);
; }
; __device__ __forceinline__ void finishSM(f32x16& p0, f32x16& p1, float alpha, float& l_reg, bf16x8& pa0, bf16x8& pa1, bf16x8& pa2, bf16x8& pa3) {
; #pragma unroll
;   for (int r = 0; r < 16; ++r) p1[r] = __builtin_amdgcn_exp2f(p1[r]);
;   float ps = 0;
; #pragma unroll
;   for (int r = 0; r < 16; ++r) ps += p0[r];
; #pragma unroll
;   for (int r = 0; r < 16; ++r) ps += p1[r];
;   { auto rr = __builtin_amdgcn_permlane32_swap(__float_as_uint(ps), __float_as_uint(ps), false, false);
;     ps = __uint_as_float(rr[0]) + __uint_as_float(rr[1]); }
;   l_reg = l_reg * alpha + ps;
;     ...
;   PK4(p0, 0, pa0); PK4(p0, 8, pa1); PK4(p1, 0, pa2); PK4(p1, 8, pa3);
;     ...
; }
; template <int DQK> __device__ __forceinline__ void qkt(f32x16& p0, f32x16& p1, const char* Ks, const bf16x8* qr, int r32, int hi, const f32x16& negm) {
; #pragma unroll
;   for (int d0 = 0; d0 < DQK / 16; ++d0) { const int cb = (d0 * 16 + hi * 8) * 2;
;     const bf16x8 b0 = *reinterpret_cast<const bf16x8*>(Ks + (DQK == 128 ? KSWZ(r32, cb) : KSWZ64(r32, cb)));
;     const bf16x8 b1 = *reinterpret_cast<const bf16x8*>(Ks + (DQK == 128 ? KSWZ(32 + r32, cb) : KSWZ64(32 + r32, cb)));
;     if (d0 == 0) { p0 = __builtin_amdgcn_mfma_f32_32x32x16_bf16(b0, qr[0], negm, 0, 0, 0); p1 = __builtin_amdgcn_mfma_f32_32x32x16_bf16(b1, qr[0], negm, 0, 0, 0); }
;     else { p0 = __builtin_amdgcn_mfma_f32_32x32x16_bf16(b0, qr[d0], p0, 0, 0, 0); p1 = __builtin_amdgcn_mfma_f32_32x32x16_bf16(b1, qr[d0], p1, 0, 0, 0); } }
; }
; template <bool BIAS, bool VIRT> __device__ __forceinline__ void fixup(f32x16& p0, f32x16& p1, int t, int L, int qw0, int r32, int hi, const float* lut) {
;     ...
;   if (__builtin_expect(k0 + KVBLK > L, 0)) {
.LBB0_76:
	s_add_i32 s14, s12, 0x80
	v_exp_f32_e32 v178, v130
	v_exp_f32_e32 v205, v131
	v_exp_f32_e32 v179, v132
	v_exp_f32_e32 v204, v133
	v_exp_f32_e32 v180, v134
	v_exp_f32_e32 v203, v135
	v_exp_f32_e32 v181, v136
	v_exp_f32_e32 v202, v137
	v_exp_f32_e32 v182, v138
	v_exp_f32_e32 v201, v139
	v_exp_f32_e32 v183, v140
	v_exp_f32_e32 v200, v141
	v_exp_f32_e32 v184, v142
	v_exp_f32_e32 v199, v143
	v_exp_f32_e32 v185, v144
	v_exp_f32_e32 v198, v145
	s_waitcnt lgkmcnt(0)
	s_barrier
	s_cmp_le_u32 s14, s16
	s_cbranch_scc0 .Lslow_g2
	ds_read_b128 v[232:235], v195 offset:40960
	ds_read_b128 v[236:239], v195 offset:32768
	ds_read_b128 v[244:247], v211 offset:40960
	ds_read_b128 v[240:243], v211 offset:32768
	v_add_f32_e32 v230, 0, v178
	v_add_f32_e32 v230, v205, v230
	v_cvt_pk_bf16_f32 v178, v178, v205
	v_add_f32_e32 v230, v179, v230
	v_add_f32_e32 v230, v204, v230
	v_cvt_pk_bf16_f32 v179, v179, v204
	v_add_f32_e32 v230, v180, v230
	v_add_f32_e32 v230, v203, v230
	v_cvt_pk_bf16_f32 v180, v180, v203
	v_add_f32_e32 v230, v181, v230
	v_add_f32_e32 v230, v202, v230
	v_cvt_pk_bf16_f32 v181, v181, v202
	s_waitcnt lgkmcnt(3)
	v_mfma_f32_32x32x16_bf16 v[98:113], v[232:235], v[174:177], v[82:97]
	v_add_f32_e32 v230, v182, v230
	v_add_f32_e32 v230, v201, v230
	v_cvt_pk_bf16_f32 v182, v182, v201
	v_add_f32_e32 v230, v183, v230
	v_add_f32_e32 v230, v200, v230
	s_waitcnt lgkmcnt(2)
	v_mfma_f32_32x32x16_bf16 v[130:145], v[236:239], v[174:177], v[82:97]
	ds_read_b128 v[232:235], v210 offset:40960
	ds_read_b128 v[236:239], v210 offset:32768
	v_cvt_pk_bf16_f32 v183, v183, v200
	v_add_f32_e32 v230, v184, v230
	v_add_f32_e32 v230, v199, v230
	v_cvt_pk_bf16_f32 v184, v184, v199
	v_add_f32_e32 v230, v185, v230
	s_waitcnt lgkmcnt(3)
	v_mfma_f32_32x32x16_bf16 v[98:113], v[244:247], v[170:173], v[98:113]
	v_add_f32_e32 v230, v198, v230
	v_cvt_pk_bf16_f32 v185, v185, v198
	v_exp_f32_e32 v114, v114
	v_exp_f32_e32 v115, v115
	v_permlane32_swap_b32_e32 v178, v180
	s_waitcnt lgkmcnt(2)
	v_mfma_f32_32x32x16_bf16 v[130:145], v[240:243], v[170:173], v[130:145]
	ds_read_b128 v[244:247], v197 offset:40960
	ds_read_b128 v[240:243], v197 offset:32768
	v_permlane32_swap_b32_e32 v179, v181
	v_permlane32_swap_b32_e32 v182, v184
	v_permlane32_swap_b32_e32 v183, v185
	v_exp_f32_e32 v116, v116
	v_add_f32_e32 v230, v114, v230
	s_waitcnt lgkmcnt(3)
	v_mfma_f32_32x32x16_bf16 v[98:113], v[232:235], v[166:169], v[98:113]
	v_exp_f32_e32 v117, v117
	v_add_f32_e32 v230, v115, v230
	v_exp_f32_e32 v118, v118
	v_add_f32_e32 v230, v116, v230
	s_waitcnt lgkmcnt(2)
	v_mfma_f32_32x32x16_bf16 v[130:145], v[236:239], v[166:169], v[130:145]
	ds_read_b128 v[232:235], v196 offset:40960
	ds_read_b128 v[236:239], v196 offset:32768
	v_exp_f32_e32 v119, v119
	v_add_f32_e32 v230, v117, v230
	v_exp_f32_e32 v120, v120
	v_add_f32_e32 v230, v118, v230
	s_waitcnt lgkmcnt(3)
	v_mfma_f32_32x32x16_bf16 v[98:113], v[244:247], v[162:165], v[98:113]
	v_exp_f32_e32 v121, v121
	v_add_f32_e32 v230, v119, v230
	v_exp_f32_e32 v122, v122
	v_add_f32_e32 v230, v120, v230
	s_waitcnt lgkmcnt(2)
	v_mfma_f32_32x32x16_bf16 v[130:145], v[240:243], v[162:165], v[130:145]
	ds_read_b128 v[244:247], v222 offset:40960
	ds_read_b128 v[240:243], v222 offset:32768
	v_exp_f32_e32 v123, v123
	v_add_f32_e32 v230, v121, v230
	v_exp_f32_e32 v124, v124
	v_add_f32_e32 v230, v122, v230
	s_waitcnt lgkmcnt(3)
	v_mfma_f32_32x32x16_bf16 v[98:113], v[232:235], v[158:161], v[98:113]
	v_exp_f32_e32 v125, v125
	v_add_f32_e32 v230, v123, v230
	v_exp_f32_e32 v126, v126
	v_add_f32_e32 v230, v124, v230
	s_waitcnt lgkmcnt(2)
	v_mfma_f32_32x32x16_bf16 v[130:145], v[236:239], v[158:161], v[130:145]
	ds_read_b128 v[232:235], v223 offset:40960
	ds_read_b128 v[236:239], v223 offset:32768
	v_exp_f32_e32 v127, v127
	v_add_f32_e32 v230, v125, v230
	v_exp_f32_e32 v128, v128
	v_add_f32_e32 v230, v126, v230
	s_waitcnt lgkmcnt(3)
	v_mfma_f32_32x32x16_bf16 v[98:113], v[244:247], v[154:157], v[98:113]
	v_exp_f32_e32 v129, v129
	v_add_f32_e32 v230, v127, v230
	v_add_f32_e32 v230, v128, v230
	v_add_f32_e32 v230, v129, v230
	s_waitcnt lgkmcnt(2)
	v_mfma_f32_32x32x16_bf16 v[130:145], v[240:243], v[154:157], v[130:145]
	ds_read_b128 v[244:247], v224 offset:40960
	ds_read_b128 v[240:243], v224 offset:32768
	v_mov_b32_e32 v231, v230
	v_cvt_pk_bf16_f32 v198, v114, v115
	v_cvt_pk_bf16_f32 v199, v116, v117
	v_cvt_pk_bf16_f32 v200, v118, v119
	s_waitcnt lgkmcnt(3)
	v_mfma_f32_32x32x16_bf16 v[98:113], v[232:235], v[150:153], v[98:113]
	v_cvt_pk_bf16_f32 v201, v120, v121
	v_cvt_pk_bf16_f32 v202, v122, v123
	v_cvt_pk_bf16_f32 v203, v124, v125
	v_cvt_pk_bf16_f32 v204, v126, v127
	s_waitcnt lgkmcnt(2)
; #define SBAR() __builtin_amdgcn_sched_barrier(0)
; #define SLOAD(i, k0) do { sr_[i].vs0 = GLD8(&Vh[(long)((k0) + sr) * LD + sc]); sr_[i].vs1 = GLD8(&Vh[(long)((k0) + 32 + sr) * LD + sc]); \
;     if (DQK == 128) { sr_[i].ks0 = GLD8(&Kh[(long)((k0) + sr) * LD + sc]); sr_[i].ks1 = GLD8(&Kh[(long)((k0) + 32 + sr) * LD + sc]); } \
;     else { sr_[i].ks0 = GLD8(&Kh[(long)((k0) + kr) * LD + kc]); } } while (0)
; template <bool FIRST> __device__ __forceinline__ void partialSM(f32x16& p0, f32x16& p1, float& m_reg, float& alpha, f32x16& negm, float c_cur) {
;   float pmax = p0[0];
; #pragma unroll
;   for (int r = 1; r < 16; ++r) pmax = fmaxf(pmax, p0[r]);
; #pragma unroll
;   for (int r = 0; r < 16; ++r) pmax = fmaxf(pmax, p1[r]);
;   { auto rr = __builtin_amdgcn_permlane32_swap(__float_as_uint(pmax), __float_as_uint(pmax), false, false);
;     pmax = fmaxf(__uint_as_float(rr[0]), __uint_as_float(rr[1])); }
; template <int D0> __device__ __forceinline__ void pv_one(f32x16& od, int vb, bf16x8 pa0, bf16x8 pa1, bf16x8 pa2, bf16x8 pa3) {
;   const s16x4 l0 = tr_read<v_rd_off(D0, 0, 0)>(vb), h0 = tr_read<v_rd_off(D0, 0, 1)>(vb), l1 = tr_read<v_rd_off(D0, 1, 0)>(vb), h1 = tr_read<v_rd_off(D0, 1, 1)>(vb);
;   const s16x4 l2 = tr_read<v_rd_off(D0, 2, 0)>(vb), h2 = tr_read<v_rd_off(D0, 2, 1)>(vb), l3 = tr_read<v_rd_off(D0, 3, 0)>(vb), h3 = tr_read<v_rd_off(D0, 3, 1)>(vb);
;   asm volatile("s_waitcnt lgkmcnt(0)" ::: "memory"); SBAR();
;     ...
;   od = __builtin_amdgcn_mfma_f32_32x32x16_bf16(pa0, PK(l0, h0), od, 0, 0, 0);
;   od = __builtin_amdgcn_mfma_f32_32x32x16_bf16(pa1, PK(l1, h1), od, 0, 0, 0);
;   od = __builtin_amdgcn_mfma_f32_32x32x16_bf16(pa2, PK(l2, h2), od, 0, 0, 0);
;   od = __builtin_amdgcn_mfma_f32_32x32x16_bf16(pa3, PK(l3, h3), od, 0, 0, 0);
;     ...
; }
; __device__ __forceinline__ void pv_d0(f32x16* o, int vb, bf16x8 pa0, bf16x8 pa1, bf16x8 pa2, bf16x8 pa3) {
;   pv_one<0>(o[0], vb, pa0, pa1, pa2, pa3); pv_one<1>(o[1], vb, pa0, pa1, pa2, pa3); pv_one<2>(o[2], vb, pa0, pa1, pa2, pa3); pv_one<3>(o[3], vb, pa0, pa1, pa2, pa3);
; template <int DQK, bool BIAS, bool VIRT = false>
; __device__ __forceinline__ void attn_pass(const bf16_t* __restrict__ Qb, const bf16_t* __restrict__ Kh, const bf16_t* __restrict__ Vh, int L, int NT, int qw0, const float* lut, f32x16 (&o)[4], char* lds, int nact) {
;     ...
;     if (SDEPTH == 1 || j + 3 < NT) SLOAD(SE, (j + 1 + SDEPTH) * KVBLK); SBAR();
	v_mfma_f32_32x32x16_bf16 v[130:145], v[236:239], v[150:153], v[130:145]
	ds_read_b64_tr_b16 v[206:207], v190 offset:0
	ds_read_b64_tr_b16 v[208:209], v190 offset:0x800
	ds_read_b64_tr_b16 v[232:233], v190 offset:0x200
	ds_read_b64_tr_b16 v[234:235], v190 offset:0xa00
	ds_read_b64_tr_b16 v[236:237], v190 offset:0x400
	ds_read_b64_tr_b16 v[238:239], v190 offset:0xc00
	v_cvt_pk_bf16_f32 v205, v128, v129
	v_permlane32_swap_b32_e32 v230, v231
	v_permlane32_swap_b32_e32 v198, v200
	v_permlane32_swap_b32_e32 v199, v201
	s_waitcnt lgkmcnt(7)
	v_mfma_f32_32x32x16_bf16 v[98:113], v[244:247], v[146:149], v[98:113]
	v_permlane32_swap_b32_e32 v202, v204
	v_permlane32_swap_b32_e32 v203, v205
	s_mov_b64 s[98:99], 0x90000
	v_lshl_add_u64 v[218:219], v[186:187], 0, s[98:99]
	s_waitcnt lgkmcnt(6)
	v_mfma_f32_32x32x16_bf16 v[130:145], v[240:243], v[146:149], v[130:145]
	ds_read_b64_tr_b16 v[240:241], v190 offset:0x600
	ds_read_b64_tr_b16 v[242:243], v190 offset:0xe00
	global_load_dwordx4 v[114:117], v[218:219], off offset:512
	global_load_dwordx4 v[118:121], v[218:219], off
	s_waitcnt lgkmcnt(6)
	v_mfma_f32_32x32x16_bf16 v[2:17], v[178:181], v[206:209], v[2:17]
	ds_read_b64_tr_b16 v[206:207], v190 offset:0x1000
	ds_read_b64_tr_b16 v[208:209], v190 offset:0x1800
	s_mov_b64 s[98:99], 0xd8000
	v_lshl_add_u64 v[218:219], v[186:187], 0, s[98:99]
	global_load_dwordx4 v[126:129], v[218:219], off offset:512
	global_load_dwordx4 v[122:125], v[218:219], off
	s_waitcnt lgkmcnt(6)
	v_mfma_f32_32x32x16_bf16 v[50:65], v[178:181], v[232:235], v[50:65]
	ds_read_b64_tr_b16 v[232:233], v190 offset:0x1200
	ds_read_b64_tr_b16 v[234:235], v190 offset:0x1a00
	s_waitcnt lgkmcnt(6)
	v_mfma_f32_32x32x16_bf16 v[34:49], v[178:181], v[236:239], v[34:49]
	ds_read_b64_tr_b16 v[236:237], v190 offset:0x1400
	ds_read_b64_tr_b16 v[238:239], v190 offset:0x1c00
	s_waitcnt lgkmcnt(6)
	v_mfma_f32_32x32x16_bf16 v[18:33], v[178:181], v[240:243], v[18:33]
	ds_read_b64_tr_b16 v[240:241], v190 offset:0x1600
	ds_read_b64_tr_b16 v[242:243], v190 offset:0x1e00
	s_waitcnt lgkmcnt(6)
	v_mfma_f32_32x32x16_bf16 v[2:17], v[182:185], v[206:209], v[2:17]
	ds_read_b64_tr_b16 v[206:207], v190 offset:0x2000
	ds_read_b64_tr_b16 v[208:209], v190 offset:0x2800
	v_max_f32_e32 v218, v130, v131
	v_max3_f32 v218, v218, v132, v133
	s_waitcnt lgkmcnt(6)
	v_mfma_f32_32x32x16_bf16 v[50:65], v[182:185], v[232:235], v[50:65]
	ds_read_b64_tr_b16 v[232:233], v190 offset:0x2200
	ds_read_b64_tr_b16 v[234:235], v190 offset:0x2a00
	v_max3_f32 v218, v218, v134, v135
	v_max3_f32 v218, v218, v136, v137
	s_waitcnt lgkmcnt(6)
	v_mfma_f32_32x32x16_bf16 v[34:49], v[182:185], v[236:239], v[34:49]
	ds_read_b64_tr_b16 v[236:237], v190 offset:0x2400
	ds_read_b64_tr_b16 v[238:239], v190 offset:0x2c00
	v_max3_f32 v218, v218, v138, v139
	v_max3_f32 v218, v218, v140, v141
	s_waitcnt lgkmcnt(6)
	v_mfma_f32_32x32x16_bf16 v[18:33], v[182:185], v[240:243], v[18:33]
	ds_read_b64_tr_b16 v[240:241], v190 offset:0x2600
	ds_read_b64_tr_b16 v[242:243], v190 offset:0x2e00
	v_max3_f32 v218, v218, v142, v143
	v_max3_f32 v218, v218, v144, v145
	s_waitcnt lgkmcnt(6)
	v_mfma_f32_32x32x16_bf16 v[2:17], v[198:201], v[206:209], v[2:17]
	ds_read_b64_tr_b16 v[206:207], v190 offset:0x3000
	ds_read_b64_tr_b16 v[208:209], v190 offset:0x3800
	v_max3_f32 v218, v218, v98, v99
	v_max3_f32 v218, v218, v100, v101
	s_waitcnt lgkmcnt(6)
	v_mfma_f32_32x32x16_bf16 v[50:65], v[198:201], v[232:235], v[50:65]
	ds_read_b64_tr_b16 v[232:233], v190 offset:0x3200
	ds_read_b64_tr_b16 v[234:235], v190 offset:0x3a00
	v_max3_f32 v218, v218, v102, v103
	v_max3_f32 v218, v218, v104, v105
	s_waitcnt lgkmcnt(6)
	v_mfma_f32_32x32x16_bf16 v[34:49], v[198:201], v[236:239], v[34:49]
	ds_read_b64_tr_b16 v[236:237], v190 offset:0x3400
	ds_read_b64_tr_b16 v[238:239], v190 offset:0x3c00
	v_max3_f32 v218, v218, v106, v107
	s_waitcnt lgkmcnt(6)
	v_mfma_f32_32x32x16_bf16 v[18:33], v[198:201], v[240:243], v[18:33]
	ds_read_b64_tr_b16 v[240:241], v190 offset:0x3600
	ds_read_b64_tr_b16 v[242:243], v190 offset:0x3e00
	v_max3_f32 v218, v218, v108, v109
	s_waitcnt lgkmcnt(6)
	v_mfma_f32_32x32x16_bf16 v[2:17], v[202:205], v[206:209], v[2:17]
	v_max3_f32 v218, v218, v110, v111
	s_waitcnt lgkmcnt(4)
	v_mfma_f32_32x32x16_bf16 v[50:65], v[202:205], v[232:235], v[50:65]
	v_max3_f32 v218, v218, v112, v113
	s_waitcnt lgkmcnt(2)
	v_mfma_f32_32x32x16_bf16 v[34:49], v[202:205], v[236:239], v[34:49]
	v_mov_b32_e32 v219, v218
	s_waitcnt lgkmcnt(0)
	v_mfma_f32_32x32x16_bf16 v[18:33], v[202:205], v[240:243], v[18:33]
	v_permlane32_swap_b32_e32 v218, v219
	v_max_f32_e32 v179, v218, v219
